# P3 epilogue: row sum-of-squares prefetched one tile ahead; epilogue head waits vmcnt(8) instead of draining the LDS-DMA queue with vmcnt(0)
# baseline (speedup 1.0000x reference)
; #define PG8_STAGE(bufoff, gbase, voff) do { _Pragma("unroll") for (int _i = 0; _i < 2; ++_i) \
;         __builtin_amdgcn_global_load_lds((const unsigned*)((const char*)(gbase) + (voff)[_i]), (PG8_LAS unsigned*)(lds + (bufoff) + ldsw + _i * 8192), 16, 0, 0); } while (0)
; #define PG8_WAIT_V(n) asm volatile("s_waitcnt vmcnt(" #n ")" ::: "memory")
; #define PG8_BAR __builtin_amdgcn_s_barrier()
; template <class Epi, class Sched, bool ALIGN_EPI = false, bool SP2 = false>
; __device__ __forceinline__ void gemm_phase(PG8_LAS unsigned char* lds, const Gemm g, const Sched& S, const Epi& E) {
;     ...
;     if constexpr (SP2) {
;         PG8_STAGE(PG8_SB(0, 0), cB, voffB); PG8_STAGE(PG8_SB(0, 1), cB + hstep, voffB); PG8_STAGE(PG8_SA(0, 0), cA, voffA); PG8_STAGE(PG8_SA(0, 1), cA + hstep, voffA);
;         if (wr == 1) PG8_BAR;
;         PG8_WAIT_V(2); PG8_BAR;
;         PG8_STAGE(PG8_SB(1, 0), cB + kstep, voffB); PG8_STAGE(PG8_SA(1, 0), cA + kstep, voffA); PG8_STAGE(PG8_SB(1, 1), cB + hstep + kstep, voffB);
;         PG8_WAIT_V(6); PG8_BAR;
;     } else {
;         PG8_STAGE(PG8_SB(0, 0), cB, voffB); PG8_STAGE(PG8_SA(0, 0), cA, voffA); PG8_STAGE(PG8_SB(0, 1), cB + hstep, voffB); PG8_STAGE(PG8_SA(0, 1), cA + hstep, voffA);
;         if (wr == 1) PG8_BAR;
;         PG8_WAIT_V(4); PG8_BAR;
;         PG8_STAGE(PG8_SB(1, 0), cB + kstep, voffB); PG8_STAGE(PG8_SA(1, 0), cA + kstep, voffA); PG8_STAGE(PG8_SB(1, 1), cB + hstep + kstep, voffB);
;         PG8_WAIT_V(6); PG8_BAR;
;     }
;     DI void operator()(const f32x4 (&acc)[2][2][4][2], const Unit& u, int wr, int wc, int fr, int fq) const {
;         const int row0 = u.pm * 256 + wr * 64 + fr, cw = wc * 32 + 8 * fq;
; #pragma unroll
;         for (int ai = 0; ai < 2; ++ai)
; #pragma unroll
;             for (int m = 0; m < 4; ++m) {
;                 const int row = row0 + ai * 128 + m * 16; const float rs = row_rstd<16>(P, row, 1.0f / 1024.0f);
.LBB0_626:
	v_bfe_u32 v13, v196, 4, 2
	v_lshlrev_b32_e32 v15, 4, v13
	v_lshlrev_b32_e32 v16, 6, v196
	s_movk_i32 s1, 0x3c0
	v_and_or_b32 v16, v16, s1, v15
	s_ashr_i32 s1, s86, 31
	v_writelane_b32 v248, s1, 6
	s_mov_b32 s1, s86
	v_writelane_b32 v248, s1, 7
	s_ashr_i32 s1, s96, 31
	s_add_u32 s52, s68, 0x3600000
	v_writelane_b32 v248, s96, 8
	s_addc_u32 s53, s69, 0
	v_writelane_b32 v248, s1, 9
	s_add_u32 s1, s68, 0x6300000
	s_addc_u32 s43, s69, 0
	s_add_u32 s15, s68, 0x7300000
	s_addc_u32 s35, s69, 0
	s_add_u32 s82, s68, 0x8300000
	s_addc_u32 s83, s69, 0
	s_add_u32 s12, s68, 0x8f00000
	s_addc_u32 s13, s69, 0
	v_writelane_b32 v248, s12, 10
	v_and_b32_e32 v12, 15, v196
	v_lshlrev_b32_e32 v17, 2, v196
	v_writelane_b32 v248, s13, 11
	s_add_u32 s12, s68, 0x9700000
	s_addc_u32 s13, s69, 0
	s_add_u32 s80, s68, 0x3800000
	s_addc_u32 s81, s69, 0
	s_add_u32 s44, s68, 0x3a00000
	v_writelane_b32 v248, s12, 12
	s_addc_u32 s45, s69, 0
	s_mov_b64 s[92:93], 0x80
	v_writelane_b32 v248, s13, 13
	s_add_u32 s12, s68, 0x3b00000
	s_addc_u32 s13, s69, 0
	v_writelane_b32 v248, s12, 14
	v_and_b32_e32 v17, 32, v17
	v_lshl_or_b32 v129, s0, 6, v12
	v_writelane_b32 v248, s13, 15
	s_add_u32 s12, s68, 0x3c00000
	s_addc_u32 s13, s69, 0
	s_and_b32 s97, s5, 3
	v_lshl_or_b32 v12, v12, 6, v15
	s_lshl_b32 s0, s0, 13
	s_add_i32 m0, s51, 0x18000
	v_lshl_add_u64 v[6:7], v[6:7], 0, s[92:93]
	v_writelane_b32 v248, s12, 16
	v_bitop3_b32 v12, v12, s0, v17 bitop3:0xde
	s_lshl_b32 s0, s97, 12
	s_waitcnt vmcnt(2)
	s_barrier
	global_load_lds_dwordx4 v[6:7], off
	v_lshl_add_u64 v[4:5], v[4:5], 0, s[92:93]
	s_add_i32 m0, s51, 0x1a000
	s_add_i32 s70, s51, 0x8000
	s_add_i32 s71, s51, 0xa000
	v_writelane_b32 v248, s13, 17
	global_load_lds_dwordx4 v[4:5], off
	v_lshl_add_u64 v[0:1], v[0:1], 0, s[92:93]
	s_mov_b32 m0, s70
	s_add_u32 s12, s8, 0x40080
	global_load_lds_dwordx4 v[0:1], off
	v_lshl_add_u64 v[0:1], v[2:3], 0, s[92:93]
	s_mov_b32 m0, s71
	s_addc_u32 s13, s9, 0
	global_load_lds_dwordx4 v[0:1], off
	s_add_i32 m0, s51, 0x1c000
	v_lshl_add_u64 v[0:1], s[12:13], 0, v[134:135]
	global_load_lds_dwordx4 v[0:1], off
	v_lshl_add_u64 v[0:1], s[12:13], 0, v[138:139]
	s_add_i32 m0, s51, 0x1e000
	s_cmpk_lt_u32 s4, 0x100
	global_load_lds_dwordx4 v[0:1], off
	s_cselect_b64 s[4:5], -1, 0
	v_writelane_b32 v248, s4, 18
	v_lshlrev_b32_e32 v140, 5, v13
	s_mov_b64 s[12:13], 0x3d00000
	v_writelane_b32 v248, s5, 19
	v_writelane_b32 v248, s68, 20
	s_waitcnt vmcnt(6)
	s_cmp_eq_u32 s97, 0
	v_lshlrev_b32_e32 v14, 3, v13
	v_lshl_add_u64 v[0:1], s[68:69], 0, v[140:141]
	v_lshl_add_u64 v[144:145], v[0:1], 0, s[12:13]
	v_lshlrev_b32_e32 v0, 4, v11
	v_and_b32_e32 v0, 0x78000, v0
	v_lshlrev_b32_e32 v1, 11, v10
	v_or3_b32 v0, v8, v0, v1
	v_add_u32_e32 v146, v0, v9
	v_lshlrev_b32_e32 v0, 8, v196
	v_and_b32_e32 v0, 0x38000, v0
	v_or3_b32 v0, v8, v0, v1
	v_bitop3_b32 v131, s0, v16, v17 bitop3:0xf6
	s_cselect_b64 s[4:5], -1, 0
	v_add_u32_e32 v148, v0, v9
	s_add_i32 s74, 0, 0x10000
	s_add_i32 s75, 0, 0x14000
	s_movk_i32 s20, 0xf600
	s_movk_i32 s22, 0xf900
	v_mbcnt_lo_u32_b32 v0, -1, 0
	v_cmp_eq_u32_e64 s[2:3], 0, v13
	v_lshl_or_b32 v142, s97, 5, v14
	v_mov_b32_e32 v147, v141
	v_mov_b32_e32 v149, v141
	v_mov_b64_e32 v[150:151], 0x240
	v_mov_b64_e32 v[152:153], 0x23f
	v_add_u32_e32 v143, s74, v131
	v_add_u32_e32 v172, s75, v131
	v_add_u32_e32 v173, 0, v12
	v_mov_b32_e32 v174, 0x358637bd
	s_movk_i32 s33, 0x300
	s_mov_b32 s14, 0x3e6d3388
	s_mov_b32 s42, 0x3f07dc22
	s_mov_b32 s96, 0xbf3a00e3
	s_mov_b32 s0, 0x3f35f0e3
	s_mov_b32 s50, 0xbe11a98e
	s_mov_b32 s34, 0x3e027906
	s_mov_b32 s46, 0xbf38aa3b
	s_xor_b64 s[72:73], s[4:5], -1
	s_mov_b32 s21, -1
	s_mov_b32 s23, -1
	v_mbcnt_hi_u32_b32 v175, -1, v0
	s_mov_b32 s36, 0
	s_barrier
	v_writelane_b32 v248, s69, 21
	v_lshl_add_u32 v234, s6, 8, v129
	v_ashrrev_i32_e32 v235, 31, v234
	v_lshl_add_u64 v[234:235], v[234:235], 2, s[52:53]
	global_load_dword v236, v[234:235], off
	global_load_dword v237, v[234:235], off offset:64
	global_load_dword v238, v[234:235], off offset:128
	global_load_dword v239, v[234:235], off offset:192
	global_load_dword v240, v[234:235], off offset:512
	global_load_dword v241, v[234:235], off offset:576
	global_load_dword v242, v[234:235], off offset:640
	global_load_dword v243, v[234:235], off offset:704
	s_nop 0
	s_nop 0
	s_nop 0
	s_branch .LBB0_629

;     DI void operator()(const f32x4 (&acc)[2][2][4][2], const Unit& u, int wr, int wc, int fr, int fq) const {
;         const int row0 = u.pm * 256 + wr * 64 + fr, cw = wc * 32 + 8 * fq;
; #pragma unroll
;         for (int ai = 0; ai < 2; ++ai)
; #pragma unroll
;             for (int m = 0; m < 4; ++m) {
;                 const int row = row0 + ai * 128 + m * 16; const float rs = row_rstd<16>(P, row, 1.0f / 1024.0f);
; #pragma unroll
;                 for (int bj = 0; bj < 2; ++bj) {
;                     const int c128 = u.pn * 256 + bj * 128;
;                     float v[8];
; #pragma unroll
;                     for (int n = 0; n < 2; ++n)
; #pragma unroll
;                         for (int i = 0; i < 4; ++i) v[4 * n + i] = acc[ai][bj][m][n][i] * rs;
;                     if (c128 < 1024) {
.LBB0_635:
	v_lshl_add_u32 v154, s6, 8, v129
	v_ashrrev_i32_e32 v155, 31, v154
	v_lshl_add_u64 v[156:157], v[154:155], 2, s[52:53]
	s_waitcnt vmcnt(8)
	v_mov_b32_e32 v244, v236
	v_mov_b32_e32 v245, v237
	v_mov_b32_e32 v246, v238
	v_mov_b32_e32 v247, v239
	v_mov_b32_e32 v250, v240
	v_mov_b32_e32 v251, v241
	v_mov_b32_e32 v252, v242
	v_mov_b32_e32 v253, v243
	v_lshl_add_u32 v234, s68, 8, v129
	v_ashrrev_i32_e32 v235, 31, v234
	v_lshl_add_u64 v[234:235], v[234:235], 2, s[52:53]
	global_load_dword v236, v[234:235], off
	global_load_dword v237, v[234:235], off offset:64
	global_load_dword v238, v[234:235], off offset:128
	global_load_dword v239, v[234:235], off offset:192
	global_load_dword v240, v[234:235], off offset:512
	global_load_dword v241, v[234:235], off offset:576
	global_load_dword v242, v[234:235], off offset:640
	global_load_dword v243, v[234:235], off offset:704
	s_nop 0
	s_nop 0
	s_lshl_b32 s94, s60, 8
	s_cmp_gt_i32 s60, 3
	s_cselect_b64 s[10:11], -1, 0
	s_mov_b64 s[44:45], s[72:73]
	s_mov_b64 s[72:73], s[84:85]
	s_mov_b64 s[86:87], s[18:19]
	s_mov_b64 s[6:7], -1
	v_mad_i64_i32 v[160:161], s[8:9], v154, s33, 0
	v_lshlrev_b64 v[158:159], 10, v[154:155]
	v_lshlrev_b64 v[164:165], 6, v[154:155]
	v_lshlrev_b64 v[162:163], 9, v[154:155]
	s_and_b64 vcc, exec, s[10:11]
	s_mov_b64 s[84:85], s[16:17]
	s_waitcnt lgkmcnt(0)
	v_fmamk_f32 v140, v244, 0x3a800000, v174
	v_rsq_f32_e32 v166, v140
	s_nop 0
	v_pk_mul_f32 v[168:169], v[124:125], v[166:167] op_sel_hi:[1,0]
	v_pk_mul_f32 v[126:127], v[126:127], v[166:167] op_sel_hi:[1,0]
	v_pk_mul_f32 v[124:125], v[120:121], v[166:167] op_sel_hi:[1,0]
	v_pk_mul_f32 v[122:123], v[122:123], v[166:167] op_sel_hi:[1,0]
	s_cbranch_vccz .LBB0_652
	s_cmpk_gt_u32 s94, 0x87f
	s_cbranch_scc1 .LBB0_651
	s_cmpk_gt_u32 s94, 0x57f
	s_cbranch_scc0 .LBB0_643
	s_cmpk_gt_u32 s94, 0x67f
	s_cbranch_scc0 .LBB0_640
	v_readlane_b32 s6, v248, 12
	v_readlane_b32 s7, v248, 13
	s_add_i32 s48, s94, 0xfffff980
	s_nop 0
	v_lshl_add_u64 v[120:121], s[6:7], 0, v[158:159]
	v_readlane_b32 s6, v248, 16
	v_readlane_b32 s7, v248, 17
	v_lshl_add_u64 v[170:171], s[48:49], 1, v[120:121]
	s_lshr_b32 s48, s48, 3
	v_lshl_add_u64 v[120:121], s[6:7], 0, v[164:165]
	v_lshl_add_u64 v[120:121], v[120:121], 0, s[48:49]
	s_lshl_b32 s48, s97, 2
	v_lshl_add_u64 v[120:121], v[120:121], 0, s[48:49]
	s_mov_b64 s[6:7], 0

;     DI void operator()(const f32x4 (&acc)[2][2][4][2], const Unit& u, int wr, int wc, int fr, int fq) const {
;     ...
; #pragma unroll
;             for (int m = 0; m < 4; ++m) {
;                 const int row = row0 + ai * 128 + m * 16; const float rs = row_rstd<16>(P, row, 1.0f / 1024.0f);
; #pragma unroll
;                 for (int bj = 0; bj < 2; ++bj) {
;                     const int c128 = u.pn * 256 + bj * 128;
;                     float v[8];
; #pragma unroll
;                     for (int n = 0; n < 2; ++n)
; #pragma unroll
;                         for (int i = 0; i < 4; ++i) v[4 * n + i] = acc[ai][bj][m][n][i] * rs;
;                     if (c128 < 1024) {
.LBB0_683:
	s_waitcnt lgkmcnt(0)
	v_or_b32_e32 v114, 16, v154
	v_ashrrev_i32_e32 v115, 31, v114
	v_lshl_add_u64 v[112:113], v[114:115], 2, s[52:53]
	s_nop 0
	v_cndmask_b32_e64 v112, 0, 1, s[10:11]
	v_mad_i64_i32 v[116:117], s[6:7], v114, s33, 0
	v_cmp_ne_u32_e64 s[8:9], 1, v112
	v_lshlrev_b64 v[112:113], 10, v[114:115]
	v_lshlrev_b64 v[120:121], 6, v[114:115]
	s_andn2_b64 vcc, exec, s[10:11]
	s_mov_b64 s[6:7], -1
	s_waitcnt lgkmcnt(0)
	v_fmamk_f32 v118, v245, 0x3a800000, v174
	v_rsq_f32_e32 v122, v118
	v_lshlrev_b64 v[118:119], 9, v[114:115]
	v_pk_mul_f32 v[124:125], v[108:109], v[122:123] op_sel_hi:[1,0]
	v_pk_mul_f32 v[110:111], v[110:111], v[122:123] op_sel_hi:[1,0]
	v_pk_mul_f32 v[108:109], v[104:105], v[122:123] op_sel_hi:[1,0]
	v_pk_mul_f32 v[106:107], v[106:107], v[122:123] op_sel_hi:[1,0]
	s_cbranch_vccnz .LBB0_700
	s_cmpk_gt_u32 s94, 0x87f
	s_cbranch_scc1 .LBB0_699
	s_cmpk_lt_u32 s94, 0x580
	s_cbranch_scc1 .LBB0_691
	s_cmpk_lt_u32 s94, 0x680
	s_cbranch_scc1 .LBB0_688
	v_readlane_b32 s6, v248, 12
	v_readlane_b32 s7, v248, 13
	s_add_i32 s48, s94, 0xfffff980
	s_nop 0
	v_lshl_add_u64 v[104:105], s[6:7], 0, v[112:113]
	v_readlane_b32 s6, v248, 16
	v_readlane_b32 s7, v248, 17
	v_lshl_add_u64 v[126:127], s[48:49], 1, v[104:105]
	s_lshr_b32 s48, s48, 3
	v_lshl_add_u64 v[104:105], s[6:7], 0, v[120:121]
	v_lshl_add_u64 v[104:105], v[104:105], 0, s[48:49]
	s_lshl_b32 s48, s97, 2
	v_lshl_add_u64 v[104:105], v[104:105], 0, s[48:49]
	s_mov_b64 s[6:7], 0

;     DI void operator()(const f32x4 (&acc)[2][2][4][2], const Unit& u, int wr, int wc, int fr, int fq) const {
;     ...
; #pragma unroll
;             for (int m = 0; m < 4; ++m) {
;                 const int row = row0 + ai * 128 + m * 16; const float rs = row_rstd<16>(P, row, 1.0f / 1024.0f);
; #pragma unroll
;                 for (int bj = 0; bj < 2; ++bj) {
;                     const int c128 = u.pn * 256 + bj * 128;
;                     float v[8];
; #pragma unroll
;                     for (int n = 0; n < 2; ++n)
; #pragma unroll
;                         for (int i = 0; i < 4; ++i) v[4 * n + i] = acc[ai][bj][m][n][i] * rs;
;                     if (c128 < 1024) {
.LBB0_731:
	s_waitcnt lgkmcnt(0)
	v_or_b32_e32 v98, 32, v154
	v_ashrrev_i32_e32 v99, 31, v98
	v_lshl_add_u64 v[96:97], v[98:99], 2, s[52:53]
	s_nop 0
	v_mad_i64_i32 v[100:101], s[10:11], v98, s33, 0
	s_and_b64 vcc, exec, s[8:9]
	v_lshlrev_b64 v[104:105], 6, v[98:99]
	v_lshlrev_b64 v[102:103], 9, v[98:99]
	s_mov_b64 s[10:11], -1
	s_waitcnt lgkmcnt(0)
	v_fmamk_f32 v96, v246, 0x3a800000, v174
	v_rsq_f32_e32 v106, v96
	v_lshlrev_b64 v[96:97], 10, v[98:99]
	v_pk_mul_f32 v[108:109], v[92:93], v[106:107] op_sel_hi:[1,0]
	v_pk_mul_f32 v[94:95], v[94:95], v[106:107] op_sel_hi:[1,0]
	v_pk_mul_f32 v[92:93], v[88:89], v[106:107] op_sel_hi:[1,0]
	v_pk_mul_f32 v[90:91], v[90:91], v[106:107] op_sel_hi:[1,0]
	s_cbranch_vccnz .LBB0_748
	s_cmpk_gt_u32 s94, 0x87f
	s_cbranch_scc1 .LBB0_747
	s_cmpk_lt_u32 s94, 0x580
	s_cbranch_scc1 .LBB0_739
	s_cmpk_lt_u32 s94, 0x680
	s_cbranch_scc1 .LBB0_736
	v_readlane_b32 s10, v248, 12
	v_readlane_b32 s11, v248, 13
	s_add_i32 s48, s94, 0xfffff980
	s_nop 0
	v_lshl_add_u64 v[88:89], s[10:11], 0, v[96:97]
	v_readlane_b32 s10, v248, 16
	v_readlane_b32 s11, v248, 17
	v_lshl_add_u64 v[110:111], s[48:49], 1, v[88:89]
	s_lshr_b32 s48, s48, 3
	v_lshl_add_u64 v[88:89], s[10:11], 0, v[104:105]
	v_lshl_add_u64 v[88:89], v[88:89], 0, s[48:49]
	s_lshl_b32 s48, s97, 2
	v_lshl_add_u64 v[88:89], v[88:89], 0, s[48:49]
	s_mov_b64 s[10:11], 0

;     DI void operator()(const f32x4 (&acc)[2][2][4][2], const Unit& u, int wr, int wc, int fr, int fq) const {
;     ...
; #pragma unroll
;             for (int m = 0; m < 4; ++m) {
;                 const int row = row0 + ai * 128 + m * 16; const float rs = row_rstd<16>(P, row, 1.0f / 1024.0f);
; #pragma unroll
;                 for (int bj = 0; bj < 2; ++bj) {
;                     const int c128 = u.pn * 256 + bj * 128;
;                     float v[8];
; #pragma unroll
;                     for (int n = 0; n < 2; ++n)
; #pragma unroll
;                         for (int i = 0; i < 4; ++i) v[4 * n + i] = acc[ai][bj][m][n][i] * rs;
;                     if (c128 < 1024) {
.LBB0_779:
	s_waitcnt lgkmcnt(0)
	v_or_b32_e32 v82, 48, v154
	v_ashrrev_i32_e32 v83, 31, v82
	v_lshl_add_u64 v[80:81], v[82:83], 2, s[52:53]
	s_nop 0
	v_mad_i64_i32 v[84:85], s[10:11], v82, s33, 0
	s_and_b64 vcc, exec, s[8:9]
	v_lshlrev_b64 v[88:89], 6, v[82:83]
	v_lshlrev_b64 v[86:87], 9, v[82:83]
	s_mov_b64 s[10:11], -1
	s_waitcnt lgkmcnt(0)
	v_fmamk_f32 v80, v247, 0x3a800000, v174
	v_rsq_f32_e32 v90, v80
	v_lshlrev_b64 v[80:81], 10, v[82:83]
	v_pk_mul_f32 v[92:93], v[76:77], v[90:91] op_sel_hi:[1,0]
	v_pk_mul_f32 v[78:79], v[78:79], v[90:91] op_sel_hi:[1,0]
	v_pk_mul_f32 v[76:77], v[72:73], v[90:91] op_sel_hi:[1,0]
	v_pk_mul_f32 v[74:75], v[74:75], v[90:91] op_sel_hi:[1,0]
	s_cbranch_vccnz .LBB0_796
	s_cmpk_gt_u32 s94, 0x87f
	s_cbranch_scc1 .LBB0_795
	s_cmpk_lt_u32 s94, 0x580
	s_cbranch_scc1 .LBB0_787
	s_cmpk_lt_u32 s94, 0x680
	s_cbranch_scc1 .LBB0_784
	v_readlane_b32 s10, v248, 12
	v_readlane_b32 s11, v248, 13
	s_add_i32 s48, s94, 0xfffff980
	s_nop 0
	v_lshl_add_u64 v[72:73], s[10:11], 0, v[80:81]
	v_readlane_b32 s10, v248, 16
	v_readlane_b32 s11, v248, 17
	v_lshl_add_u64 v[94:95], s[48:49], 1, v[72:73]
	s_lshr_b32 s48, s48, 3
	v_lshl_add_u64 v[72:73], s[10:11], 0, v[88:89]
	v_lshl_add_u64 v[72:73], v[72:73], 0, s[48:49]
	s_lshl_b32 s48, s97, 2
	v_lshl_add_u64 v[72:73], v[72:73], 0, s[48:49]
	s_mov_b64 s[10:11], 0

;     DI void operator()(const f32x4 (&acc)[2][2][4][2], const Unit& u, int wr, int wc, int fr, int fq) const {
;     ...
; #pragma unroll
;             for (int m = 0; m < 4; ++m) {
;                 const int row = row0 + ai * 128 + m * 16; const float rs = row_rstd<16>(P, row, 1.0f / 1024.0f);
; #pragma unroll
;                 for (int bj = 0; bj < 2; ++bj) {
;                     const int c128 = u.pn * 256 + bj * 128;
;                     float v[8];
; #pragma unroll
;                     for (int n = 0; n < 2; ++n)
; #pragma unroll
;                         for (int i = 0; i < 4; ++i) v[4 * n + i] = acc[ai][bj][m][n][i] * rs;
;                     if (c128 < 1024) {
.LBB0_827:
	s_nop 0
	s_waitcnt lgkmcnt(0)
	v_add_u32_e32 v66, 0x80, v154
	v_ashrrev_i32_e32 v67, 31, v66
	v_mad_i64_i32 v[68:69], s[10:11], v66, s33, 0
	s_and_b64 vcc, exec, s[8:9]
	v_lshlrev_b64 v[72:73], 6, v[66:67]
	v_lshlrev_b64 v[70:71], 9, v[66:67]
	s_mov_b64 s[10:11], -1
	v_fmamk_f32 v64, v250, 0x3a800000, v174
	v_rsq_f32_e32 v74, v64
	v_lshlrev_b64 v[64:65], 10, v[66:67]
	v_pk_mul_f32 v[76:77], v[60:61], v[74:75] op_sel_hi:[1,0]
	v_pk_mul_f32 v[62:63], v[62:63], v[74:75] op_sel_hi:[1,0]
	v_pk_mul_f32 v[60:61], v[56:57], v[74:75] op_sel_hi:[1,0]
	v_pk_mul_f32 v[58:59], v[58:59], v[74:75] op_sel_hi:[1,0]
	s_cbranch_vccnz .LBB0_844
	s_cmpk_gt_u32 s94, 0x87f
	s_cbranch_scc1 .LBB0_843
	s_cmpk_lt_u32 s94, 0x580
	s_cbranch_scc1 .LBB0_835
	s_cmpk_lt_u32 s94, 0x680
	s_cbranch_scc1 .LBB0_832
	v_readlane_b32 s10, v248, 12
	v_readlane_b32 s11, v248, 13
	s_add_i32 s48, s94, 0xfffff980
	s_nop 0
	v_lshl_add_u64 v[56:57], s[10:11], 0, v[64:65]
	v_readlane_b32 s10, v248, 16
	v_readlane_b32 s11, v248, 17
	v_lshl_add_u64 v[78:79], s[48:49], 1, v[56:57]
	s_lshr_b32 s48, s48, 3
	v_lshl_add_u64 v[56:57], s[10:11], 0, v[72:73]
	v_lshl_add_u64 v[56:57], v[56:57], 0, s[48:49]
	s_lshl_b32 s48, s97, 2
	v_lshl_add_u64 v[56:57], v[56:57], 0, s[48:49]
	s_mov_b64 s[10:11], 0

;     DI void operator()(const f32x4 (&acc)[2][2][4][2], const Unit& u, int wr, int wc, int fr, int fq) const {
;     ...
; #pragma unroll
;             for (int m = 0; m < 4; ++m) {
;                 const int row = row0 + ai * 128 + m * 16; const float rs = row_rstd<16>(P, row, 1.0f / 1024.0f);
; #pragma unroll
;                 for (int bj = 0; bj < 2; ++bj) {
;                     const int c128 = u.pn * 256 + bj * 128;
;                     float v[8];
; #pragma unroll
;                     for (int n = 0; n < 2; ++n)
; #pragma unroll
;                         for (int i = 0; i < 4; ++i) v[4 * n + i] = acc[ai][bj][m][n][i] * rs;
;                     if (c128 < 1024) {
.LBB0_875:
	s_nop 0
	s_waitcnt lgkmcnt(0)
	v_add_u32_e32 v50, 0x90, v154
	v_ashrrev_i32_e32 v51, 31, v50
	v_mad_i64_i32 v[52:53], s[10:11], v50, s33, 0
	s_and_b64 vcc, exec, s[8:9]
	v_lshlrev_b64 v[56:57], 6, v[50:51]
	v_lshlrev_b64 v[54:55], 9, v[50:51]
	s_mov_b64 s[10:11], -1
	v_fmamk_f32 v48, v251, 0x3a800000, v174
	v_rsq_f32_e32 v58, v48
	v_lshlrev_b64 v[48:49], 10, v[50:51]
	v_pk_mul_f32 v[60:61], v[44:45], v[58:59] op_sel_hi:[1,0]
	v_pk_mul_f32 v[46:47], v[46:47], v[58:59] op_sel_hi:[1,0]
	v_pk_mul_f32 v[44:45], v[40:41], v[58:59] op_sel_hi:[1,0]
	v_pk_mul_f32 v[42:43], v[42:43], v[58:59] op_sel_hi:[1,0]
	s_cbranch_vccnz .LBB0_892
	s_cmpk_gt_u32 s94, 0x87f
	s_cbranch_scc1 .LBB0_891
	s_cmpk_lt_u32 s94, 0x580
	s_cbranch_scc1 .LBB0_883
	s_cmpk_lt_u32 s94, 0x680
	s_cbranch_scc1 .LBB0_880
	v_readlane_b32 s10, v248, 12
	v_readlane_b32 s11, v248, 13
	s_add_i32 s48, s94, 0xfffff980
	s_nop 0
	v_lshl_add_u64 v[40:41], s[10:11], 0, v[48:49]
	v_readlane_b32 s10, v248, 16
	v_readlane_b32 s11, v248, 17
	v_lshl_add_u64 v[62:63], s[48:49], 1, v[40:41]
	s_lshr_b32 s48, s48, 3
	v_lshl_add_u64 v[40:41], s[10:11], 0, v[56:57]
	v_lshl_add_u64 v[40:41], v[40:41], 0, s[48:49]
	s_lshl_b32 s48, s97, 2
	v_lshl_add_u64 v[40:41], v[40:41], 0, s[48:49]
	s_mov_b64 s[10:11], 0

;     DI void operator()(const f32x4 (&acc)[2][2][4][2], const Unit& u, int wr, int wc, int fr, int fq) const {
;     ...
; #pragma unroll
;             for (int m = 0; m < 4; ++m) {
;                 const int row = row0 + ai * 128 + m * 16; const float rs = row_rstd<16>(P, row, 1.0f / 1024.0f);
; #pragma unroll
;                 for (int bj = 0; bj < 2; ++bj) {
;                     const int c128 = u.pn * 256 + bj * 128;
;                     float v[8];
; #pragma unroll
;                     for (int n = 0; n < 2; ++n)
; #pragma unroll
;                         for (int i = 0; i < 4; ++i) v[4 * n + i] = acc[ai][bj][m][n][i] * rs;
;                     if (c128 < 1024) {
.LBB0_923:
	s_nop 0
	s_waitcnt lgkmcnt(0)
	v_add_u32_e32 v34, 0xa0, v154
	v_ashrrev_i32_e32 v35, 31, v34
	v_mad_i64_i32 v[36:37], s[10:11], v34, s33, 0
	s_and_b64 vcc, exec, s[8:9]
	v_lshlrev_b64 v[40:41], 6, v[34:35]
	v_lshlrev_b64 v[38:39], 9, v[34:35]
	s_mov_b64 s[10:11], -1
	v_fmamk_f32 v32, v252, 0x3a800000, v174
	v_rsq_f32_e32 v42, v32
	v_lshlrev_b64 v[32:33], 10, v[34:35]
	v_pk_mul_f32 v[44:45], v[28:29], v[42:43] op_sel_hi:[1,0]
	v_pk_mul_f32 v[30:31], v[30:31], v[42:43] op_sel_hi:[1,0]
	v_pk_mul_f32 v[28:29], v[24:25], v[42:43] op_sel_hi:[1,0]
	v_pk_mul_f32 v[26:27], v[26:27], v[42:43] op_sel_hi:[1,0]
	s_cbranch_vccnz .LBB0_940
	s_cmpk_gt_u32 s94, 0x87f
	s_cbranch_scc1 .LBB0_939
	s_cmpk_lt_u32 s94, 0x580
	s_cbranch_scc1 .LBB0_931
	s_cmpk_lt_u32 s94, 0x680
	s_cbranch_scc1 .LBB0_928
	v_readlane_b32 s10, v248, 12
	v_readlane_b32 s11, v248, 13
	s_add_i32 s48, s94, 0xfffff980
	s_nop 0
	v_lshl_add_u64 v[24:25], s[10:11], 0, v[32:33]
	v_readlane_b32 s10, v248, 16
	v_readlane_b32 s11, v248, 17
	v_lshl_add_u64 v[46:47], s[48:49], 1, v[24:25]
	s_lshr_b32 s48, s48, 3
	v_lshl_add_u64 v[24:25], s[10:11], 0, v[40:41]
	v_lshl_add_u64 v[24:25], v[24:25], 0, s[48:49]
	s_lshl_b32 s48, s97, 2
	v_lshl_add_u64 v[24:25], v[24:25], 0, s[48:49]
	s_mov_b64 s[10:11], 0

;     DI void operator()(const f32x4 (&acc)[2][2][4][2], const Unit& u, int wr, int wc, int fr, int fq) const {
;     ...
; #pragma unroll
;             for (int m = 0; m < 4; ++m) {
;                 const int row = row0 + ai * 128 + m * 16; const float rs = row_rstd<16>(P, row, 1.0f / 1024.0f);
; #pragma unroll
;                 for (int bj = 0; bj < 2; ++bj) {
;                     const int c128 = u.pn * 256 + bj * 128;
;                     float v[8];
; #pragma unroll
;                     for (int n = 0; n < 2; ++n)
; #pragma unroll
;                         for (int i = 0; i < 4; ++i) v[4 * n + i] = acc[ai][bj][m][n][i] * rs;
;                     if (c128 < 1024) {
.LBB0_971:
	s_nop 0
	s_waitcnt lgkmcnt(0)
	v_add_u32_e32 v18, 0xb0, v154
	s_and_b64 vcc, exec, s[8:9]
	v_ashrrev_i32_e32 v19, 31, v18
	v_mad_i64_i32 v[20:21], s[8:9], v18, s33, 0
	v_lshlrev_b64 v[24:25], 6, v[18:19]
	v_lshlrev_b64 v[22:23], 9, v[18:19]
	s_mov_b64 s[8:9], -1
	v_fmamk_f32 v16, v253, 0x3a800000, v174
	v_rsq_f32_e32 v26, v16
	v_lshlrev_b64 v[16:17], 10, v[18:19]
	v_pk_mul_f32 v[28:29], v[12:13], v[26:27] op_sel_hi:[1,0]
	v_pk_mul_f32 v[14:15], v[14:15], v[26:27] op_sel_hi:[1,0]
	v_pk_mul_f32 v[12:13], v[8:9], v[26:27] op_sel_hi:[1,0]
	v_pk_mul_f32 v[10:11], v[10:11], v[26:27] op_sel_hi:[1,0]
	s_cbranch_vccnz .LBB0_988
	s_cmpk_gt_u32 s94, 0x87f
	s_cbranch_scc1 .LBB0_987
	s_cmpk_lt_u32 s94, 0x580
	s_cbranch_scc1 .LBB0_979
	s_cmpk_lt_u32 s94, 0x680
	s_cbranch_scc1 .LBB0_976
	v_readlane_b32 s8, v248, 12
	v_readlane_b32 s9, v248, 13
	s_add_i32 s48, s94, 0xfffff980
	s_nop 0
	v_lshl_add_u64 v[8:9], s[8:9], 0, v[16:17]
	v_readlane_b32 s8, v248, 16
	v_readlane_b32 s9, v248, 17
	v_lshl_add_u64 v[30:31], s[48:49], 1, v[8:9]
	s_lshr_b32 s48, s48, 3
	v_lshl_add_u64 v[8:9], s[8:9], 0, v[24:25]
	v_lshl_add_u64 v[8:9], v[8:9], 0, s[48:49]
	s_lshl_b32 s48, s97, 2
	v_lshl_add_u64 v[8:9], v[8:9], 0, s[48:49]
	s_mov_b64 s[8:9], 0
